# SGU task split: every operand request (W, bias, u to registers; V^T tile to LDS) at the start of the phase, MFMAs and gated gelu after the context chain
# baseline (speedup 1.0000x reference)
.Lsp3_entry:
	s_cmpk_ge_u32 s63, 0xc0
	s_cbranch_scc1 .Lsgu_pre_skip
	v_and_b32_e32 v143, 63, v206
	v_lshrrev_b32_e32 v140, 6, v206
	v_and_b32_e32 v141, 15, v143
	v_lshrrev_b32_e32 v142, 4, v143
	v_readfirstlane_b32 s40, v140
	s_lshr_b32 s41, s63, 2
	s_and_b32 s42, s63, 3
	v_lshlrev_b32_e32 v145, 8, v141
	v_lshl_add_u32 v145, v142, 4, v145
	s_lshl_b32 s43, s36, 2
	s_add_u32 s43, s43, s42
	s_lshl_b32 s100, s43, 7
	s_lshl_b32 s101, s40, 4
	s_add_u32 s100, s100, s101
	s_lshl_b32 s100, s100, 8
	s_add_u32 s100, s100, 0x2dc0000
	s_add_u32 s44, s96, s100
	s_addc_u32 s45, s97, 0
	global_load_dwordx4 v[104:107], v145, s[44:45]
	global_load_dwordx4 v[108:111], v145, s[44:45] offset:64
	global_load_dwordx4 v[112:115], v145, s[44:45] offset:128
	global_load_dwordx4 v[116:119], v145, s[44:45] offset:192
	s_lshl_b32 s100, s41, 8
	s_lshl_b32 s101, s42, 6
	s_add_u32 s100, s100, s101
	s_lshl_b32 s100, s100, 8
	s_add_u32 s100, s100, 0xc784000
	s_add_u32 s46, s96, s100
	s_addc_u32 s47, s97, 0
	s_and_b32 s100, s40, 3
	s_lshl_b32 s100, s100, 2
	v_add_u32_e32 v146, s100, v142
	v_xor_b32_e32 v146, v146, v141
	v_lshlrev_b32_e32 v146, 4, v146
	v_lshl_add_u32 v146, v142, 8, v146
	s_lshl_b32 s101, s40, 10
	s_add_u32 s46, s46, s101
	s_addc_u32 s47, s47, 0
	s_add_u32 m0, s101, 0x23010
	s_nop 0
	global_load_lds_dwordx4 v146, s[46:47]
	s_add_u32 s46, s46, 0x2000
	s_addc_u32 s47, s47, 0
	s_add_u32 m0, s101, 0x25010
	s_nop 0
	global_load_lds_dwordx4 v146, s[46:47]
	v_readlane_b32 s48, v237, 33
	v_readlane_b32 s49, v237, 34
	s_lshl_b32 s100, s43, 9
	s_lshl_b32 s101, s40, 6
	s_add_u32 s100, s100, s101
	s_add_u32 s48, s48, s100
	s_addc_u32 s49, s49, 0
	v_lshlrev_b32_e32 v143, 4, v142
	s_nop 3
	global_load_dwordx4 v[120:123], v143, s[48:49]
	s_lshl_b32 s100, s41, 7
	s_lshl_b32 s101, s40, 4
	s_add_u32 s100, s100, s101
	s_mul_i32 s50, s100, 0x2440
	s_lshl_b32 s101, s42, 8
	s_add_u32 s50, s50, s101
	s_add_u32 s50, s50, 0x3a25840
	s_add_u32 s52, s96, s50
	s_addc_u32 s53, s97, 0
	v_mul_u32_u24_e32 v144, 0x9100, v142
	v_lshl_add_u32 v144, v141, 2, v144
	global_load_dword v124, v144, s[52:53]
	global_load_dword v125, v144, s[52:53] offset:64
	global_load_dword v126, v144, s[52:53] offset:128
	global_load_dword v127, v144, s[52:53] offset:192
	v_add_u32_e32 v143, 0x2440, v144
	global_load_dword v128, v143, s[52:53]
	global_load_dword v129, v143, s[52:53] offset:64
	global_load_dword v130, v143, s[52:53] offset:128
	global_load_dword v131, v143, s[52:53] offset:192
	v_add_u32_e32 v143, 0x4880, v144
	global_load_dword v132, v143, s[52:53]
	global_load_dword v133, v143, s[52:53] offset:64
	global_load_dword v134, v143, s[52:53] offset:128
	global_load_dword v135, v143, s[52:53] offset:192
	v_add_u32_e32 v143, 0x6cc0, v144
	global_load_dword v136, v143, s[52:53]
	global_load_dword v137, v143, s[52:53] offset:64
	global_load_dword v138, v143, s[52:53] offset:128
	global_load_dword v139, v143, s[52:53] offset:192

.Lsp3_e0:
	s_cmpk_ge_u32 s63, 0xc0
	s_cbranch_scc1 .Lsp3_e2
	v_and_b32_e32 v143, 63, v206
	v_lshrrev_b32_e32 v140, 6, v206
	v_and_b32_e32 v141, 15, v143
	v_lshrrev_b32_e32 v142, 4, v143
	v_readfirstlane_b32 s40, v140
	v_add_u32_e32 v154, 0, v142
	v_xor_b32_e32 v154, v154, v141
	v_lshlrev_b32_e32 v154, 4, v154
	v_lshl_add_u32 v154, v141, 8, v154
	v_add_u32_e32 v154, 0x23010, v154
	v_add_u32_e32 v155, 4, v142
	v_xor_b32_e32 v155, v155, v141
	v_lshlrev_b32_e32 v155, 4, v155
	v_lshl_add_u32 v155, v141, 8, v155
	v_add_u32_e32 v155, 0x23010, v155
	v_add_u32_e32 v156, 8, v142
	v_xor_b32_e32 v156, v156, v141
	v_lshlrev_b32_e32 v156, 4, v156
	v_lshl_add_u32 v156, v141, 8, v156
	v_add_u32_e32 v156, 0x23010, v156
	v_add_u32_e32 v157, 12, v142
	v_xor_b32_e32 v157, v157, v141
	v_lshlrev_b32_e32 v157, 4, v157
	v_lshl_add_u32 v157, v141, 8, v157
	v_add_u32_e32 v157, 0x23010, v157
	ds_read_b128 v[20:23], v154 offset:0
	ds_read_b128 v[36:39], v155 offset:0
	ds_read_b128 v[52:55], v156 offset:0
	ds_read_b128 v[68:71], v157 offset:0
	ds_read_b128 v[24:27], v154 offset:4096
	ds_read_b128 v[40:43], v155 offset:4096
	ds_read_b128 v[56:59], v156 offset:4096
	ds_read_b128 v[72:75], v157 offset:4096
	ds_read_b128 v[28:31], v154 offset:8192
	ds_read_b128 v[44:47], v155 offset:8192
	ds_read_b128 v[60:63], v156 offset:8192
	ds_read_b128 v[76:79], v157 offset:8192
	s_waitcnt lgkmcnt(8)
	ds_read_b128 v[32:35], v154 offset:12288
	ds_read_b128 v[48:51], v155 offset:12288
	ds_read_b128 v[64:67], v156 offset:12288
	ds_read_b128 v[80:83], v157 offset:12288
	s_lshr_b32 s41, s63, 2
	s_and_b32 s42, s63, 3
	s_lshl_b32 s100, s41, 7
	s_lshl_b32 s101, s40, 4
	s_add_u32 s100, s100, s101
	s_lshl_b32 s50, s100, 11
	s_lshl_b32 s101, s42, 7
	s_add_u32 s50, s50, s101
	s_add_u32 s50, s50, 0x7084400
	s_add_u32 s54, s96, s50
	s_addc_u32 s55, s97, 0
	v_lshlrev_b32_e32 v140, 13, v142
	v_lshl_add_u32 v140, v141, 1, v140
	s_waitcnt lgkmcnt(0)
	v_mfma_f32_16x16x32_bf16 v[84:87], v[104:107], v[20:23], 0
	v_mfma_f32_16x16x32_bf16 v[88:91], v[104:107], v[24:27], 0
	v_mfma_f32_16x16x32_bf16 v[92:95], v[104:107], v[28:31], 0
	v_mfma_f32_16x16x32_bf16 v[96:99], v[104:107], v[32:35], 0
	v_mfma_f32_16x16x32_bf16 v[84:87], v[108:111], v[36:39], v[84:87]
	v_mfma_f32_16x16x32_bf16 v[88:91], v[108:111], v[40:43], v[88:91]
	v_mfma_f32_16x16x32_bf16 v[92:95], v[108:111], v[44:47], v[92:95]
	v_mfma_f32_16x16x32_bf16 v[96:99], v[108:111], v[48:51], v[96:99]
	v_mfma_f32_16x16x32_bf16 v[84:87], v[112:115], v[52:55], v[84:87]
	v_mfma_f32_16x16x32_bf16 v[88:91], v[112:115], v[56:59], v[88:91]
	v_mfma_f32_16x16x32_bf16 v[92:95], v[112:115], v[60:63], v[92:95]
	v_mfma_f32_16x16x32_bf16 v[96:99], v[112:115], v[64:67], v[96:99]
	v_mfma_f32_16x16x32_bf16 v[84:87], v[116:119], v[68:71], v[84:87]
	v_mfma_f32_16x16x32_bf16 v[88:91], v[116:119], v[72:75], v[88:91]
	v_mfma_f32_16x16x32_bf16 v[92:95], v[116:119], v[76:79], v[92:95]
	v_mfma_f32_16x16x32_bf16 v[96:99], v[116:119], v[80:83], v[96:99]
	s_nop 7
	v_mul_f32_e32 v147, 0x3d372713, v124
	v_mul_f32_e32 v147, v124, v147
	v_fma_f32 v147, v124, v147, v124
	v_mul_f32_e32 v147, 0x3f4c422a, v147
	v_add_f32_e32 v147, v147, v147
	v_mul_f32_e32 v147, 0x3fb8aa3b, v147
	v_exp_f32_e32 v147, v147
	v_mul_f32_e32 v148, 0.5, v124
	v_add_f32_e32 v147, 1.0, v147
	v_div_scale_f32 v149, s[100:101], v147, v147, 2.0
	v_rcp_f32_e32 v150, v149
	s_nop 0
	v_fma_f32 v151, -v149, v150, 1.0
	v_fmac_f32_e32 v150, v151, v150
	v_div_scale_f32 v151, vcc, 2.0, v147, 2.0
	v_mul_f32_e32 v152, v151, v150
	v_fma_f32 v153, -v149, v152, v151
	v_fmac_f32_e32 v152, v153, v150
	v_fma_f32 v149, -v149, v152, v151
	v_div_fmas_f32 v149, v149, v150, v152
	v_div_fixup_f32 v147, v149, v147, 2.0
	v_sub_f32_e32 v147, 1.0, v147
	v_add_f32_e32 v147, 1.0, v147
	v_mul_f32_e32 v124, v148, v147
	v_add_f32_e32 v147, v84, v120
	v_mul_f32_e32 v124, v124, v147
	v_bfe_u32 v147, v124, 16, 1
	v_add3_u32 v124, v124, v147, s27
	global_store_short_d16_hi v140, v124, s[54:55]
	v_mul_f32_e32 v147, 0x3d372713, v125
	v_mul_f32_e32 v147, v125, v147
	v_fma_f32 v147, v125, v147, v125
	v_mul_f32_e32 v147, 0x3f4c422a, v147
	v_add_f32_e32 v147, v147, v147
	v_mul_f32_e32 v147, 0x3fb8aa3b, v147
	v_exp_f32_e32 v147, v147
	v_mul_f32_e32 v148, 0.5, v125
	v_add_f32_e32 v147, 1.0, v147
	v_div_scale_f32 v149, s[100:101], v147, v147, 2.0
	v_rcp_f32_e32 v150, v149
	s_nop 0
	v_fma_f32 v151, -v149, v150, 1.0
	v_fmac_f32_e32 v150, v151, v150
	v_div_scale_f32 v151, vcc, 2.0, v147, 2.0
	v_mul_f32_e32 v152, v151, v150
	v_fma_f32 v153, -v149, v152, v151
	v_fmac_f32_e32 v152, v153, v150
	v_fma_f32 v149, -v149, v152, v151
	v_div_fmas_f32 v149, v149, v150, v152
	v_div_fixup_f32 v147, v149, v147, 2.0
	v_sub_f32_e32 v147, 1.0, v147
	v_add_f32_e32 v147, 1.0, v147
	v_mul_f32_e32 v125, v148, v147
	v_add_f32_e32 v147, v88, v120
	v_mul_f32_e32 v125, v125, v147
	v_bfe_u32 v147, v125, 16, 1
	v_add3_u32 v125, v125, v147, s27
	global_store_short_d16_hi v140, v125, s[54:55] offset:32
	v_mul_f32_e32 v147, 0x3d372713, v126
	v_mul_f32_e32 v147, v126, v147
	v_fma_f32 v147, v126, v147, v126
	v_mul_f32_e32 v147, 0x3f4c422a, v147
	v_add_f32_e32 v147, v147, v147
	v_mul_f32_e32 v147, 0x3fb8aa3b, v147
	v_exp_f32_e32 v147, v147
	v_mul_f32_e32 v148, 0.5, v126
	v_add_f32_e32 v147, 1.0, v147
	v_div_scale_f32 v149, s[100:101], v147, v147, 2.0
	v_rcp_f32_e32 v150, v149
	s_nop 0
	v_fma_f32 v151, -v149, v150, 1.0
	v_fmac_f32_e32 v150, v151, v150
	v_div_scale_f32 v151, vcc, 2.0, v147, 2.0
	v_mul_f32_e32 v152, v151, v150
	v_fma_f32 v153, -v149, v152, v151
	v_fmac_f32_e32 v152, v153, v150
	v_fma_f32 v149, -v149, v152, v151
	v_div_fmas_f32 v149, v149, v150, v152
	v_div_fixup_f32 v147, v149, v147, 2.0
	v_sub_f32_e32 v147, 1.0, v147
	v_add_f32_e32 v147, 1.0, v147
	v_mul_f32_e32 v126, v148, v147
	v_add_f32_e32 v147, v92, v120
	v_mul_f32_e32 v126, v126, v147
	v_bfe_u32 v147, v126, 16, 1
	v_add3_u32 v126, v126, v147, s27
	global_store_short_d16_hi v140, v126, s[54:55] offset:64
	v_mul_f32_e32 v147, 0x3d372713, v127
	v_mul_f32_e32 v147, v127, v147
	v_fma_f32 v147, v127, v147, v127
	v_mul_f32_e32 v147, 0x3f4c422a, v147
	v_add_f32_e32 v147, v147, v147
	v_mul_f32_e32 v147, 0x3fb8aa3b, v147
	v_exp_f32_e32 v147, v147
	v_mul_f32_e32 v148, 0.5, v127
	v_add_f32_e32 v147, 1.0, v147
	v_div_scale_f32 v149, s[100:101], v147, v147, 2.0
	v_rcp_f32_e32 v150, v149
	s_nop 0
	v_fma_f32 v151, -v149, v150, 1.0
	v_fmac_f32_e32 v150, v151, v150
	v_div_scale_f32 v151, vcc, 2.0, v147, 2.0
	v_mul_f32_e32 v152, v151, v150
	v_fma_f32 v153, -v149, v152, v151
	v_fmac_f32_e32 v152, v153, v150
	v_fma_f32 v149, -v149, v152, v151
	v_div_fmas_f32 v149, v149, v150, v152
	v_div_fixup_f32 v147, v149, v147, 2.0
	v_sub_f32_e32 v147, 1.0, v147
	v_add_f32_e32 v147, 1.0, v147
	v_mul_f32_e32 v127, v148, v147
	v_add_f32_e32 v147, v96, v120
	v_mul_f32_e32 v127, v127, v147
	v_bfe_u32 v147, v127, 16, 1
	v_add3_u32 v127, v127, v147, s27
	global_store_short_d16_hi v140, v127, s[54:55] offset:96
	v_add_u32_e32 v143, 0x800, v140
	v_mul_f32_e32 v147, 0x3d372713, v128
	v_mul_f32_e32 v147, v128, v147
	v_fma_f32 v147, v128, v147, v128
	v_mul_f32_e32 v147, 0x3f4c422a, v147
	v_add_f32_e32 v147, v147, v147
	v_mul_f32_e32 v147, 0x3fb8aa3b, v147
	v_exp_f32_e32 v147, v147
	v_mul_f32_e32 v148, 0.5, v128
	v_add_f32_e32 v147, 1.0, v147
	v_div_scale_f32 v149, s[100:101], v147, v147, 2.0
	v_rcp_f32_e32 v150, v149
	s_nop 0
	v_fma_f32 v151, -v149, v150, 1.0
	v_fmac_f32_e32 v150, v151, v150
	v_div_scale_f32 v151, vcc, 2.0, v147, 2.0
	v_mul_f32_e32 v152, v151, v150
	v_fma_f32 v153, -v149, v152, v151
	v_fmac_f32_e32 v152, v153, v150
	v_fma_f32 v149, -v149, v152, v151
	v_div_fmas_f32 v149, v149, v150, v152
	v_div_fixup_f32 v147, v149, v147, 2.0
	v_sub_f32_e32 v147, 1.0, v147
	v_add_f32_e32 v147, 1.0, v147
	v_mul_f32_e32 v128, v148, v147
	v_add_f32_e32 v147, v85, v121
	v_mul_f32_e32 v128, v128, v147
	v_bfe_u32 v147, v128, 16, 1
	v_add3_u32 v128, v128, v147, s27
	global_store_short_d16_hi v143, v128, s[54:55]
	v_mul_f32_e32 v147, 0x3d372713, v129
	v_mul_f32_e32 v147, v129, v147
	v_fma_f32 v147, v129, v147, v129
	v_mul_f32_e32 v147, 0x3f4c422a, v147
	v_add_f32_e32 v147, v147, v147
	v_mul_f32_e32 v147, 0x3fb8aa3b, v147
	v_exp_f32_e32 v147, v147
	v_mul_f32_e32 v148, 0.5, v129
	v_add_f32_e32 v147, 1.0, v147
	v_div_scale_f32 v149, s[100:101], v147, v147, 2.0
	v_rcp_f32_e32 v150, v149
	s_nop 0
	v_fma_f32 v151, -v149, v150, 1.0
	v_fmac_f32_e32 v150, v151, v150
	v_div_scale_f32 v151, vcc, 2.0, v147, 2.0
	v_mul_f32_e32 v152, v151, v150
	v_fma_f32 v153, -v149, v152, v151
	v_fmac_f32_e32 v152, v153, v150
	v_fma_f32 v149, -v149, v152, v151
	v_div_fmas_f32 v149, v149, v150, v152
	v_div_fixup_f32 v147, v149, v147, 2.0
	v_sub_f32_e32 v147, 1.0, v147
	v_add_f32_e32 v147, 1.0, v147
	v_mul_f32_e32 v129, v148, v147
	v_add_f32_e32 v147, v89, v121
	v_mul_f32_e32 v129, v129, v147
	v_bfe_u32 v147, v129, 16, 1
	v_add3_u32 v129, v129, v147, s27
	global_store_short_d16_hi v143, v129, s[54:55] offset:32
	v_mul_f32_e32 v147, 0x3d372713, v130
	v_mul_f32_e32 v147, v130, v147
	v_fma_f32 v147, v130, v147, v130
	v_mul_f32_e32 v147, 0x3f4c422a, v147
	v_add_f32_e32 v147, v147, v147
	v_mul_f32_e32 v147, 0x3fb8aa3b, v147
	v_exp_f32_e32 v147, v147
	v_mul_f32_e32 v148, 0.5, v130
	v_add_f32_e32 v147, 1.0, v147
	v_div_scale_f32 v149, s[100:101], v147, v147, 2.0
	v_rcp_f32_e32 v150, v149
	s_nop 0
	v_fma_f32 v151, -v149, v150, 1.0
	v_fmac_f32_e32 v150, v151, v150
	v_div_scale_f32 v151, vcc, 2.0, v147, 2.0
	v_mul_f32_e32 v152, v151, v150
	v_fma_f32 v153, -v149, v152, v151
	v_fmac_f32_e32 v152, v153, v150
	v_fma_f32 v149, -v149, v152, v151
	v_div_fmas_f32 v149, v149, v150, v152
	v_div_fixup_f32 v147, v149, v147, 2.0
	v_sub_f32_e32 v147, 1.0, v147
	v_add_f32_e32 v147, 1.0, v147
	v_mul_f32_e32 v130, v148, v147
	v_add_f32_e32 v147, v93, v121
	v_mul_f32_e32 v130, v130, v147
	v_bfe_u32 v147, v130, 16, 1
	v_add3_u32 v130, v130, v147, s27
	global_store_short_d16_hi v143, v130, s[54:55] offset:64
	v_mul_f32_e32 v147, 0x3d372713, v131
	v_mul_f32_e32 v147, v131, v147
	v_fma_f32 v147, v131, v147, v131
	v_mul_f32_e32 v147, 0x3f4c422a, v147
	v_add_f32_e32 v147, v147, v147
	v_mul_f32_e32 v147, 0x3fb8aa3b, v147
	v_exp_f32_e32 v147, v147
	v_mul_f32_e32 v148, 0.5, v131
	v_add_f32_e32 v147, 1.0, v147
	v_div_scale_f32 v149, s[100:101], v147, v147, 2.0
	v_rcp_f32_e32 v150, v149
	s_nop 0
	v_fma_f32 v151, -v149, v150, 1.0
	v_fmac_f32_e32 v150, v151, v150
	v_div_scale_f32 v151, vcc, 2.0, v147, 2.0
	v_mul_f32_e32 v152, v151, v150
	v_fma_f32 v153, -v149, v152, v151
	v_fmac_f32_e32 v152, v153, v150
	v_fma_f32 v149, -v149, v152, v151
	v_div_fmas_f32 v149, v149, v150, v152
	v_div_fixup_f32 v147, v149, v147, 2.0
	v_sub_f32_e32 v147, 1.0, v147
	v_add_f32_e32 v147, 1.0, v147
	v_mul_f32_e32 v131, v148, v147
	v_add_f32_e32 v147, v97, v121
	v_mul_f32_e32 v131, v131, v147
	v_bfe_u32 v147, v131, 16, 1
	v_add3_u32 v131, v131, v147, s27
	global_store_short_d16_hi v143, v131, s[54:55] offset:96
	v_add_u32_e32 v143, 0x1000, v140
	v_mul_f32_e32 v147, 0x3d372713, v132
	v_mul_f32_e32 v147, v132, v147
	v_fma_f32 v147, v132, v147, v132
	v_mul_f32_e32 v147, 0x3f4c422a, v147
	v_add_f32_e32 v147, v147, v147
	v_mul_f32_e32 v147, 0x3fb8aa3b, v147
	v_exp_f32_e32 v147, v147
	v_mul_f32_e32 v148, 0.5, v132
	v_add_f32_e32 v147, 1.0, v147
	v_div_scale_f32 v149, s[100:101], v147, v147, 2.0
	v_rcp_f32_e32 v150, v149
	s_nop 0
	v_fma_f32 v151, -v149, v150, 1.0
	v_fmac_f32_e32 v150, v151, v150
	v_div_scale_f32 v151, vcc, 2.0, v147, 2.0
	v_mul_f32_e32 v152, v151, v150
	v_fma_f32 v153, -v149, v152, v151
	v_fmac_f32_e32 v152, v153, v150
	v_fma_f32 v149, -v149, v152, v151
	v_div_fmas_f32 v149, v149, v150, v152
	v_div_fixup_f32 v147, v149, v147, 2.0
	v_sub_f32_e32 v147, 1.0, v147
	v_add_f32_e32 v147, 1.0, v147
	v_mul_f32_e32 v132, v148, v147
	v_add_f32_e32 v147, v86, v122
	v_mul_f32_e32 v132, v132, v147
	v_bfe_u32 v147, v132, 16, 1
	v_add3_u32 v132, v132, v147, s27
	global_store_short_d16_hi v143, v132, s[54:55]
	v_mul_f32_e32 v147, 0x3d372713, v133
	v_mul_f32_e32 v147, v133, v147
	v_fma_f32 v147, v133, v147, v133
	v_mul_f32_e32 v147, 0x3f4c422a, v147
	v_add_f32_e32 v147, v147, v147
	v_mul_f32_e32 v147, 0x3fb8aa3b, v147
	v_exp_f32_e32 v147, v147
	v_mul_f32_e32 v148, 0.5, v133
	v_add_f32_e32 v147, 1.0, v147
	v_div_scale_f32 v149, s[100:101], v147, v147, 2.0
	v_rcp_f32_e32 v150, v149
	s_nop 0
	v_fma_f32 v151, -v149, v150, 1.0
	v_fmac_f32_e32 v150, v151, v150
	v_div_scale_f32 v151, vcc, 2.0, v147, 2.0
	v_mul_f32_e32 v152, v151, v150
	v_fma_f32 v153, -v149, v152, v151
	v_fmac_f32_e32 v152, v153, v150
	v_fma_f32 v149, -v149, v152, v151
	v_div_fmas_f32 v149, v149, v150, v152
	v_div_fixup_f32 v147, v149, v147, 2.0
	v_sub_f32_e32 v147, 1.0, v147
	v_add_f32_e32 v147, 1.0, v147
	v_mul_f32_e32 v133, v148, v147
	v_add_f32_e32 v147, v90, v122
	v_mul_f32_e32 v133, v133, v147
	v_bfe_u32 v147, v133, 16, 1
	v_add3_u32 v133, v133, v147, s27
	global_store_short_d16_hi v143, v133, s[54:55] offset:32
	v_mul_f32_e32 v147, 0x3d372713, v134
	v_mul_f32_e32 v147, v134, v147
	v_fma_f32 v147, v134, v147, v134
	v_mul_f32_e32 v147, 0x3f4c422a, v147
	v_add_f32_e32 v147, v147, v147
	v_mul_f32_e32 v147, 0x3fb8aa3b, v147
	v_exp_f32_e32 v147, v147
	v_mul_f32_e32 v148, 0.5, v134
	v_add_f32_e32 v147, 1.0, v147
	v_div_scale_f32 v149, s[100:101], v147, v147, 2.0
	v_rcp_f32_e32 v150, v149
	s_nop 0
	v_fma_f32 v151, -v149, v150, 1.0
	v_fmac_f32_e32 v150, v151, v150
	v_div_scale_f32 v151, vcc, 2.0, v147, 2.0
	v_mul_f32_e32 v152, v151, v150
	v_fma_f32 v153, -v149, v152, v151
	v_fmac_f32_e32 v152, v153, v150
	v_fma_f32 v149, -v149, v152, v151
	v_div_fmas_f32 v149, v149, v150, v152
	v_div_fixup_f32 v147, v149, v147, 2.0
	v_sub_f32_e32 v147, 1.0, v147
	v_add_f32_e32 v147, 1.0, v147
	v_mul_f32_e32 v134, v148, v147
	v_add_f32_e32 v147, v94, v122
	v_mul_f32_e32 v134, v134, v147
	v_bfe_u32 v147, v134, 16, 1
	v_add3_u32 v134, v134, v147, s27
	global_store_short_d16_hi v143, v134, s[54:55] offset:64
	v_mul_f32_e32 v147, 0x3d372713, v135
	v_mul_f32_e32 v147, v135, v147
	v_fma_f32 v147, v135, v147, v135
	v_mul_f32_e32 v147, 0x3f4c422a, v147
	v_add_f32_e32 v147, v147, v147
	v_mul_f32_e32 v147, 0x3fb8aa3b, v147
	v_exp_f32_e32 v147, v147
	v_mul_f32_e32 v148, 0.5, v135
	v_add_f32_e32 v147, 1.0, v147
	v_div_scale_f32 v149, s[100:101], v147, v147, 2.0
	v_rcp_f32_e32 v150, v149
	s_nop 0
	v_fma_f32 v151, -v149, v150, 1.0
	v_fmac_f32_e32 v150, v151, v150
	v_div_scale_f32 v151, vcc, 2.0, v147, 2.0
	v_mul_f32_e32 v152, v151, v150
	v_fma_f32 v153, -v149, v152, v151
	v_fmac_f32_e32 v152, v153, v150
	v_fma_f32 v149, -v149, v152, v151
	v_div_fmas_f32 v149, v149, v150, v152
	v_div_fixup_f32 v147, v149, v147, 2.0
	v_sub_f32_e32 v147, 1.0, v147
	v_add_f32_e32 v147, 1.0, v147
	v_mul_f32_e32 v135, v148, v147
	v_add_f32_e32 v147, v98, v122
	v_mul_f32_e32 v135, v135, v147
	v_bfe_u32 v147, v135, 16, 1
	v_add3_u32 v135, v135, v147, s27
	global_store_short_d16_hi v143, v135, s[54:55] offset:96
	v_add_u32_e32 v143, 0x1800, v140
	v_mul_f32_e32 v147, 0x3d372713, v136
	v_mul_f32_e32 v147, v136, v147
	v_fma_f32 v147, v136, v147, v136
	v_mul_f32_e32 v147, 0x3f4c422a, v147
	v_add_f32_e32 v147, v147, v147
	v_mul_f32_e32 v147, 0x3fb8aa3b, v147
	v_exp_f32_e32 v147, v147
	v_mul_f32_e32 v148, 0.5, v136
	v_add_f32_e32 v147, 1.0, v147
	v_div_scale_f32 v149, s[100:101], v147, v147, 2.0
	v_rcp_f32_e32 v150, v149
	s_nop 0
	v_fma_f32 v151, -v149, v150, 1.0
	v_fmac_f32_e32 v150, v151, v150
	v_div_scale_f32 v151, vcc, 2.0, v147, 2.0
	v_mul_f32_e32 v152, v151, v150
	v_fma_f32 v153, -v149, v152, v151
	v_fmac_f32_e32 v152, v153, v150
	v_fma_f32 v149, -v149, v152, v151
	v_div_fmas_f32 v149, v149, v150, v152
	v_div_fixup_f32 v147, v149, v147, 2.0
	v_sub_f32_e32 v147, 1.0, v147
	v_add_f32_e32 v147, 1.0, v147
	v_mul_f32_e32 v136, v148, v147
	v_add_f32_e32 v147, v87, v123
	v_mul_f32_e32 v136, v136, v147
	v_bfe_u32 v147, v136, 16, 1
	v_add3_u32 v136, v136, v147, s27
	global_store_short_d16_hi v143, v136, s[54:55]
	v_mul_f32_e32 v147, 0x3d372713, v137
	v_mul_f32_e32 v147, v137, v147
	v_fma_f32 v147, v137, v147, v137
	v_mul_f32_e32 v147, 0x3f4c422a, v147
	v_add_f32_e32 v147, v147, v147
	v_mul_f32_e32 v147, 0x3fb8aa3b, v147
	v_exp_f32_e32 v147, v147
	v_mul_f32_e32 v148, 0.5, v137
	v_add_f32_e32 v147, 1.0, v147
	v_div_scale_f32 v149, s[100:101], v147, v147, 2.0
	v_rcp_f32_e32 v150, v149
	s_nop 0
	v_fma_f32 v151, -v149, v150, 1.0
	v_fmac_f32_e32 v150, v151, v150
	v_div_scale_f32 v151, vcc, 2.0, v147, 2.0
	v_mul_f32_e32 v152, v151, v150
	v_fma_f32 v153, -v149, v152, v151
	v_fmac_f32_e32 v152, v153, v150
	v_fma_f32 v149, -v149, v152, v151
	v_div_fmas_f32 v149, v149, v150, v152
	v_div_fixup_f32 v147, v149, v147, 2.0
	v_sub_f32_e32 v147, 1.0, v147
	v_add_f32_e32 v147, 1.0, v147
	v_mul_f32_e32 v137, v148, v147
	v_add_f32_e32 v147, v91, v123
	v_mul_f32_e32 v137, v137, v147
	v_bfe_u32 v147, v137, 16, 1
	v_add3_u32 v137, v137, v147, s27
	global_store_short_d16_hi v143, v137, s[54:55] offset:32
	v_mul_f32_e32 v147, 0x3d372713, v138
	v_mul_f32_e32 v147, v138, v147
	v_fma_f32 v147, v138, v147, v138
	v_mul_f32_e32 v147, 0x3f4c422a, v147
	v_add_f32_e32 v147, v147, v147
	v_mul_f32_e32 v147, 0x3fb8aa3b, v147
	v_exp_f32_e32 v147, v147
	v_mul_f32_e32 v148, 0.5, v138
	v_add_f32_e32 v147, 1.0, v147
	v_div_scale_f32 v149, s[100:101], v147, v147, 2.0
	v_rcp_f32_e32 v150, v149
	s_nop 0
	v_fma_f32 v151, -v149, v150, 1.0
	v_fmac_f32_e32 v150, v151, v150
	v_div_scale_f32 v151, vcc, 2.0, v147, 2.0
	v_mul_f32_e32 v152, v151, v150
	v_fma_f32 v153, -v149, v152, v151
	v_fmac_f32_e32 v152, v153, v150
	v_fma_f32 v149, -v149, v152, v151
	v_div_fmas_f32 v149, v149, v150, v152
	v_div_fixup_f32 v147, v149, v147, 2.0
	v_sub_f32_e32 v147, 1.0, v147
	v_add_f32_e32 v147, 1.0, v147
	v_mul_f32_e32 v138, v148, v147
	v_add_f32_e32 v147, v95, v123
	v_mul_f32_e32 v138, v138, v147
	v_bfe_u32 v147, v138, 16, 1
	v_add3_u32 v138, v138, v147, s27
	global_store_short_d16_hi v143, v138, s[54:55] offset:64
	v_mul_f32_e32 v147, 0x3d372713, v139
	v_mul_f32_e32 v147, v139, v147
	v_fma_f32 v147, v139, v147, v139
	v_mul_f32_e32 v147, 0x3f4c422a, v147
	v_add_f32_e32 v147, v147, v147
	v_mul_f32_e32 v147, 0x3fb8aa3b, v147
	v_exp_f32_e32 v147, v147
	v_mul_f32_e32 v148, 0.5, v139
	v_add_f32_e32 v147, 1.0, v147
	v_div_scale_f32 v149, s[100:101], v147, v147, 2.0
	v_rcp_f32_e32 v150, v149
	s_nop 0
	v_fma_f32 v151, -v149, v150, 1.0
	v_fmac_f32_e32 v150, v151, v150
	v_div_scale_f32 v151, vcc, 2.0, v147, 2.0
	v_mul_f32_e32 v152, v151, v150
	v_fma_f32 v153, -v149, v152, v151
	v_fmac_f32_e32 v152, v153, v150
	v_fma_f32 v149, -v149, v152, v151
	v_div_fmas_f32 v149, v149, v150, v152
	v_div_fixup_f32 v147, v149, v147, 2.0
	v_sub_f32_e32 v147, 1.0, v147
	v_add_f32_e32 v147, 1.0, v147
	v_mul_f32_e32 v139, v148, v147
	v_add_f32_e32 v147, v99, v123
	v_mul_f32_e32 v139, v139, v147
	v_bfe_u32 v147, v139, 16, 1
	v_add3_u32 v139, v139, v147, s27
	global_store_short_d16_hi v143, v139, s[54:55] offset:96
	s_branch .Lsp3_e2
